# phase E q-row loop: rope-table load retargeted so its wait merges with the row loads' wait (one round trip per row), on top of RKP prefetch + 16-load hoist
# baseline (speedup 1.0000x reference)
.LBB0_772:
	s_and_b32 s3, s16, 63
	s_bitset1_b32 s3, 12
	s_cmpk_lt_i32 s16, 0x2000
	s_cselect_b32 s4, s16, s3
	s_ashr_i32 s5, s4, 31
	s_ashr_i32 s17, s16, 31
	s_lshl_b64 s[4:5], s[4:5], 8
	s_lshl_b64 s[18:19], s[16:17], 11
	v_lshl_add_u64 v[8:9], v[18:19], 0, s[4:5]
	v_lshl_add_u64 v[32:33], v[20:21], 0, s[18:19]
	global_load_dwordx4 v[4:7], v[8:9], off offset:16
	s_nop 0
	global_load_dwordx4 v[118:121], v[8:9], off
	s_nop 0
	global_load_dwordx2 v[38:39], v[32:33], off
	global_load_dwordx2 v[36:37], v[32:33], off offset:512
	global_load_dwordx2 v[34:35], v[32:33], off offset:1024
	s_nop 0
	global_load_dwordx2 v[32:33], v[32:33], off offset:1536
	v_mov_b32_e32 v40, 0x1800
	v_mad_i64_i32 v[40:41], s[4:5], s16, v40, v[16:17]
	s_mov_b32 s3, 0
	s_lshl_b64 s[20:21], s[16:17], 4
	s_mov_b64 s[22:23], -1
	s_branch .LBB0_774

.Lerow_ld_done:
	s_or_b64 exec, exec, s[24:25]
	s_waitcnt vmcnt(0)
	v_mov_b32_e32 v42, v118
	v_mov_b32_e32 v43, v120
	v_mov_b32_e32 v10, v119
	v_mov_b32_e32 v11, v121
	s_branch .Lerow_compute
